# attention: waves skip QK/softmax/PV work of key tiles that are fully causally masked for all of their 32 query rows (barriers and K/V staging kept)
# speedup vs baseline: 1.0037x; 1.0037x over previous
; #define SBAR() __builtin_amdgcn_sched_barrier(0)
; #define QK_RD(d0, sl) do { if ((d0) < 8) { const int a_ = kbase ^ (((d0) & 7) << 5); KRD(f0[sl], a_, 0); KRD(f1[sl], a_, 32 * 256); } \
;                            else { const int a_ = rbase ^ (((d0) & 3) << 5); KRD(f0[sl], a_, 0); KRD(f1[sl], a_, 32 * 128); } } while (0)
; #define PV_RD(d0, L, H) do { constexpr int b_ = v_rd_off(d0, 0, 0); TRRD(L[0], b_); TRRD(H[0], b_ + 2048); TRRD(L[1], b_ + 4096); TRRD(H[1], b_ + 6144); TRRD(L[2], b_ + 8192); TRRD(H[2], b_ + 10240); TRRD(L[3], b_ + 12288); TRRD(H[3], b_ + 14336); } while (0)
; #define LGKM(n) asm volatile("s_waitcnt lgkmcnt(" #n ")" ::: "memory")
; __device__ __forceinline__ void mphase(bool has_pv, f32x16* o, int vb, bf16x8 pa0, bf16x8 pa1, bf16x8 pa2, bf16x8 pa3, f32x16& p0, f32x16& p1, int kbase, int rbase, const bf16x8* qr) {
;     ...
;     if (has_pv) {
;         s16x4 la[4], ha[4], lb[4], hb[4];
;         PV_RD(0, la, ha); PV_RD(1, lb, hb);
;         LGKM(8); SBAR(); PV_MM(0, la, ha); SBAR();
;         PV_RD(2, la, ha); LGKM(8); SBAR(); PV_MM(1, lb, hb); SBAR();
;         PV_RD(3, lb, hb); LGKM(8); SBAR(); PV_MM(2, la, ha); SBAR();
;         LGKM(0); SBAR(); PV_MM(3, lb, hb); SBAR();
;     }
;     QK_RD(0, 0); QK_RD(1, 1);
;     p0 = f32x16{}; p1 = f32x16{};
; #pragma unroll
;     for (int d0 = 0; d0 < 12; ++d0) {
;         if (d0 + 2 < 12) { QK_RD(d0 + 2, (d0 + 2) % 3); LGKM(4); }
; __device__ __forceinline__ void attn_block(const Ptrs& P, int b, int h, int qb, LAS char* lds) {
;     ...
;     for (int x = 0; x < NT; ++x) {
;         SBAR(); __builtin_amdgcn_s_setprio(1);
;         mphase(x > 0, o, vb0 + pv3 * SHM_V, pa0, pa1, pa2, pa3, p0, p1, kbase, rbase, qr); if (x > 0) pv3 = pv3 == 2 ? 0 : pv3 + 1;
;         __builtin_amdgcn_s_setprio(0);
;         kbase ^= SHM_K; rbase ^= SHM_R;
;         __syncthreads();
.LBB0_615:
	s_setprio 1
	s_cmp_eq_u32 s81, 0
	s_cselect_b64 s[56:57], -1, 0
	s_add_i32 s22, s75, s81
	s_cmp_lt_i32 s22, -95
	s_cbranch_scc1 .Lattn_dead_m
	s_and_b64 vcc, exec, s[56:57]
	s_cbranch_vccnz .LBB0_617
	v_lshl_add_u32 v199, s83, 14, v182
	ds_read_b64_tr_b16 v[84:85], v199 offset:0x0
	ds_read_b64_tr_b16 v[86:87], v199 offset:0x800
	ds_read_b64_tr_b16 v[88:89], v199 offset:0x1000
	ds_read_b64_tr_b16 v[90:91], v199 offset:0x1800
	ds_read_b64_tr_b16 v[92:93], v199 offset:0x2000
	ds_read_b64_tr_b16 v[94:95], v199 offset:0x2800
	ds_read_b64_tr_b16 v[96:97], v199 offset:0x3000
	ds_read_b64_tr_b16 v[98:99], v199 offset:0x3800
	s_waitcnt lgkmcnt(6)
	v_mfma_f32_32x32x16_bf16 v[52:67], v[68:71], v[84:87], v[52:67]
	ds_read_b64_tr_b16 v[200:201], v199 offset:0x200
	ds_read_b64_tr_b16 v[202:203], v199 offset:0xa00
	s_waitcnt lgkmcnt(6)
	v_mfma_f32_32x32x16_bf16 v[52:67], v[72:75], v[88:91], v[52:67]
	ds_read_b64_tr_b16 v[204:205], v199 offset:0x1200
	ds_read_b64_tr_b16 v[206:207], v199 offset:0x1a00
	s_waitcnt lgkmcnt(6)
	v_mfma_f32_32x32x16_bf16 v[52:67], v[76:79], v[92:95], v[52:67]
	ds_read_b64_tr_b16 v[208:209], v199 offset:0x2200
	ds_read_b64_tr_b16 v[210:211], v199 offset:0x2a00
	s_waitcnt lgkmcnt(6)
	v_mfma_f32_32x32x16_bf16 v[52:67], v[80:83], v[96:99], v[52:67]
	ds_read_b64_tr_b16 v[212:213], v199 offset:0x3200
	ds_read_b64_tr_b16 v[214:215], v199 offset:0x3a00
	ds_read_b64_tr_b16 v[84:85], v199 offset:0x400
	ds_read_b64_tr_b16 v[86:87], v199 offset:0xc00
	s_waitcnt lgkmcnt(8)
	v_mfma_f32_32x32x16_bf16 v[36:51], v[68:71], v[200:203], v[36:51]
	ds_read_b64_tr_b16 v[88:89], v199 offset:0x1400
	ds_read_b64_tr_b16 v[90:91], v199 offset:0x1c00
	s_waitcnt lgkmcnt(8)
	v_mfma_f32_32x32x16_bf16 v[36:51], v[72:75], v[204:207], v[36:51]
	ds_read_b64_tr_b16 v[92:93], v199 offset:0x2400
	ds_read_b64_tr_b16 v[94:95], v199 offset:0x2c00
	s_waitcnt lgkmcnt(8)
	v_mfma_f32_32x32x16_bf16 v[36:51], v[76:79], v[208:211], v[36:51]
	ds_read_b64_tr_b16 v[96:97], v199 offset:0x3400
	ds_read_b64_tr_b16 v[98:99], v199 offset:0x3c00
	s_waitcnt lgkmcnt(8)
	v_mfma_f32_32x32x16_bf16 v[36:51], v[80:83], v[212:215], v[36:51]
	ds_read_b64_tr_b16 v[200:201], v199 offset:0x600
	ds_read_b64_tr_b16 v[202:203], v199 offset:0xe00
	s_waitcnt lgkmcnt(8)
	v_mfma_f32_32x32x16_bf16 v[20:35], v[68:71], v[84:87], v[20:35]
	ds_read_b64_tr_b16 v[204:205], v199 offset:0x1600
	ds_read_b64_tr_b16 v[206:207], v199 offset:0x1e00
	s_waitcnt lgkmcnt(8)
	v_mfma_f32_32x32x16_bf16 v[20:35], v[72:75], v[88:91], v[20:35]
	ds_read_b64_tr_b16 v[208:209], v199 offset:0x2600
	ds_read_b64_tr_b16 v[210:211], v199 offset:0x2e00
	s_waitcnt lgkmcnt(8)
	v_mfma_f32_32x32x16_bf16 v[20:35], v[76:79], v[92:95], v[20:35]
	ds_read_b64_tr_b16 v[212:213], v199 offset:0x3600
	ds_read_b64_tr_b16 v[214:215], v199 offset:0x3e00
	s_waitcnt lgkmcnt(8)
	v_mfma_f32_32x32x16_bf16 v[20:35], v[80:83], v[96:99], v[20:35]
	s_waitcnt lgkmcnt(6)
	v_mfma_f32_32x32x16_bf16 v[4:19], v[68:71], v[200:203], v[4:19]
	ds_read_b128 v[68:71], v3 offset:0
	s_waitcnt lgkmcnt(5)
	v_mfma_f32_32x32x16_bf16 v[4:19], v[72:75], v[204:207], v[4:19]
	ds_read_b128 v[72:75], v3 offset:0x2000
	v_xor_b32_e32 v199, 32, v3
	ds_read_b128 v[200:203], v199 offset:0
	s_waitcnt lgkmcnt(5)
	v_mfma_f32_32x32x16_bf16 v[4:19], v[76:79], v[208:211], v[4:19]
	ds_read_b128 v[204:207], v199 offset:0x2000
	s_waitcnt lgkmcnt(4)
	v_mfma_f32_32x32x16_bf16 v[4:19], v[80:83], v[212:215], v[4:19]
	v_xor_b32_e32 v76, 64, v3
	ds_read_b128 v[208:211], v76 offset:0
	ds_read_b128 v[212:215], v76 offset:0x2000
	s_cmp_lt_i32 s22, -31
	s_cbranch_scc1 .Lattn_dead_qk
	s_branch .Lattn_qk

; #define SBAR() __builtin_amdgcn_sched_barrier(0)
; __device__ __forceinline__ void attn_block(const Ptrs& P, int b, int h, int qb, LAS char* lds) {
;     ...
;         SBAR(); __builtin_amdgcn_s_setprio(1);
;         mphase(x > 0, o, vb0 + pv3 * SHM_V, pa0, pa1, pa2, pa3, p0, p1, kbase, rbase, qr); if (x > 0) pv3 = pv3 == 2 ? 0 : pv3 + 1;
;         __builtin_amdgcn_s_setprio(0);
;         kbase ^= SHM_K; rbase ^= SHM_R;
;         __syncthreads();
;     ...
;     SBAR(); __builtin_amdgcn_s_setprio(1); pv_tile(o, vb0 + pv3 * SHM_V, pa0, pa1, pa2, pa3); __builtin_amdgcn_s_setprio(0); SBAR();
;     __syncthreads();
;     if (!grp) __syncthreads();
.Lattn_dead_m:
.Lattn_dead_qk:
	s_waitcnt lgkmcnt(0)
	s_setprio 0
	s_barrier
	v_xor_b32_e32 v3, 0x4000, v3
	v_xor_b32_e32 v197, 0x2000, v197
	v_mov_b32_e32 v85, 0
	s_branch .LBB0_623
.LBB0_629:
	v_mov_b32_e32 v85, v198
	v_mov_b32_e32 v86, v198
	s_nop 1
	v_permlane32_swap_b32_e32 v85, v86
	v_add_f32_e32 v85, v85, v86
	s_add_i32 s22, s75, s81
	s_cmp_lt_i32 s22, -95
	s_cbranch_scc1 .Lattn_dead_flush
	s_setprio 1
	v_lshl_add_u32 v3, s83, 14, v182
	ds_read_b64_tr_b16 v[86:87], v3 offset:0
	ds_read_b64_tr_b16 v[88:89], v3 offset:0x800
	ds_read_b64_tr_b16 v[90:91], v3 offset:0x1000
	ds_read_b64_tr_b16 v[92:93], v3 offset:0x1800
	ds_read_b64_tr_b16 v[94:95], v3 offset:0x2000
	ds_read_b64_tr_b16 v[96:97], v3 offset:0x2800
	ds_read_b64_tr_b16 v[98:99], v3 offset:0x3000
	ds_read_b64_tr_b16 v[100:101], v3 offset:0x3800
	s_waitcnt lgkmcnt(0)
	s_nop 0
	v_mfma_f32_32x32x16_bf16 v[52:67], v[68:71], v[86:89], v[52:67]
	ds_read_b64_tr_b16 v[86:87], v3 offset:0x200
	ds_read_b64_tr_b16 v[88:89], v3 offset:0xa00
	v_mfma_f32_32x32x16_bf16 v[52:67], v[72:75], v[90:93], v[52:67]
	ds_read_b64_tr_b16 v[90:91], v3 offset:0x1200
	ds_read_b64_tr_b16 v[92:93], v3 offset:0x1a00
	v_mfma_f32_32x32x16_bf16 v[52:67], v[76:79], v[94:97], v[52:67]
	ds_read_b64_tr_b16 v[94:95], v3 offset:0x2200
	ds_read_b64_tr_b16 v[96:97], v3 offset:0x2a00
	ds_read_b64_tr_b16 v[102:103], v3 offset:0x3200
	ds_read_b64_tr_b16 v[104:105], v3 offset:0x3a00
	s_waitcnt lgkmcnt(0)
	v_mfma_f32_32x32x16_bf16 v[52:67], v[80:83], v[98:101], v[52:67]
	v_mfma_f32_32x32x16_bf16 v[36:51], v[68:71], v[86:89], v[36:51]
	ds_read_b64_tr_b16 v[86:87], v3 offset:0x400
	ds_read_b64_tr_b16 v[88:89], v3 offset:0xc00
	v_mfma_f32_32x32x16_bf16 v[36:51], v[72:75], v[90:93], v[36:51]
	ds_read_b64_tr_b16 v[90:91], v3 offset:0x1400
	ds_read_b64_tr_b16 v[92:93], v3 offset:0x1c00
	v_mfma_f32_32x32x16_bf16 v[36:51], v[76:79], v[94:97], v[36:51]
	ds_read_b64_tr_b16 v[94:95], v3 offset:0x2400
	ds_read_b64_tr_b16 v[96:97], v3 offset:0x2c00
	ds_read_b64_tr_b16 v[98:99], v3 offset:0x3400
	ds_read_b64_tr_b16 v[100:101], v3 offset:0x3c00
	s_waitcnt lgkmcnt(0)
	v_mfma_f32_32x32x16_bf16 v[36:51], v[80:83], v[102:105], v[36:51]
	v_mfma_f32_32x32x16_bf16 v[20:35], v[68:71], v[86:89], v[20:35]
	ds_read_b64_tr_b16 v[86:87], v3 offset:0x600
	ds_read_b64_tr_b16 v[88:89], v3 offset:0xe00
	v_mfma_f32_32x32x16_bf16 v[20:35], v[72:75], v[90:93], v[20:35]
	ds_read_b64_tr_b16 v[90:91], v3 offset:0x1600
	ds_read_b64_tr_b16 v[92:93], v3 offset:0x1e00
	v_mfma_f32_32x32x16_bf16 v[20:35], v[76:79], v[94:97], v[20:35]
	ds_read_b64_tr_b16 v[94:95], v3 offset:0x2600
	ds_read_b64_tr_b16 v[96:97], v3 offset:0x2e00
	ds_read_b64_tr_b16 v[102:103], v3 offset:0x3600
	ds_read_b64_tr_b16 v[104:105], v3 offset:0x3e00
	s_waitcnt lgkmcnt(0)
	v_mfma_f32_32x32x16_bf16 v[20:35], v[80:83], v[98:101], v[20:35]
	v_mfma_f32_32x32x16_bf16 v[4:19], v[68:71], v[86:89], v[4:19]
	v_mfma_f32_32x32x16_bf16 v[4:19], v[72:75], v[90:93], v[4:19]
	v_mfma_f32_32x32x16_bf16 v[4:19], v[76:79], v[94:97], v[4:19]
	v_mfma_f32_32x32x16_bf16 v[4:19], v[80:83], v[102:105], v[4:19]
	s_setprio 0
.Lattn_dead_flush:
	s_and_b64 vcc, exec, s[54:55]
	s_barrier
	s_cbranch_vccz .LBB0_631
	s_barrier
